# P4 group norm: 64 rows per workgroup with write-through stores and a per-panel counter hand-off (no redundant rows, no dirty L2 at the next barrier)
# speedup vs baseline: 1.0207x; 1.0026x over previous
; __device__ __forceinline__ unsigned xb_xcc_id() { return (unsigned)__builtin_amdgcn_s_getreg((3 << 11) | 20) & 0xFu; }
; __global__ void __launch_bounds__(512, 2) hymba_fwd(Params p) {
;     ...
;     XB xb; xb.bar = (unsigned*)(ws + OFF_BAR); xb.x = xb_xcc_id();
;     if (c == 0) for (int i = threadIdx.x; i < 2176; i += 512) xb.bar[1024 + i] = 0u;
;     if (threadIdx.x == 0) xb.bar[3200 + c] = xb.x;
_Z9hymba_fwd6Params:
	s_load_dwordx2 s[82:83], s[0:1], 0x100
	s_load_dword s33, s[0:1], 0x108
	s_add_u32 s24, s0, 0x108
	s_addc_u32 s25, s1, 0
	s_getreg_b32 s3, hwreg(HW_REG_XCC_ID, 0, 4)
	s_waitcnt lgkmcnt(0)
	s_add_u32 s4, s82, 0x1b6e900
	s_addc_u32 s5, s83, 0
	s_cmp_eq_u32 s2, 0
	v_writelane_b32 v253, s4, 0
	s_mov_b32 s8, 0
	s_cselect_b64 s[6:7], -1, 0
	s_cmp_lg_u32 s2, 0
	v_and_b32_e32 v132, 0x3ff, v0
	v_writelane_b32 v253, s5, 1
	s_cbranch_scc1 .LBB0_8
	v_cmp_eq_u32_e32 vcc, 0, v132
	s_and_saveexec_b64 s[98:99], vcc
	s_cbranch_execz .Lgs_init_done
	s_load_dwordx2 s[100:101], s[24:25], 0x58
	v_mov_b32_e32 v1, 0
	v_mov_b32_e32 v2, 0x3600
	global_store_dword v2, v1, s[4:5] offset:0 sc0 sc1
	global_store_dword v2, v1, s[4:5] offset:128 sc0 sc1
	global_store_dword v2, v1, s[4:5] offset:256 sc0 sc1
	global_store_dword v2, v1, s[4:5] offset:384 sc0 sc1
	global_store_dword v2, v1, s[4:5] offset:512 sc0 sc1
	global_store_dword v2, v1, s[4:5] offset:640 sc0 sc1
	global_store_dword v2, v1, s[4:5] offset:768 sc0 sc1
	global_store_dword v2, v1, s[4:5] offset:896 sc0 sc1
	global_store_dword v2, v1, s[4:5] offset:1024 sc0 sc1
	global_store_dword v2, v1, s[4:5] offset:1152 sc0 sc1
	global_store_dword v2, v1, s[4:5] offset:1280 sc0 sc1
	global_store_dword v2, v1, s[4:5] offset:1408 sc0 sc1
	global_store_dword v2, v1, s[4:5] offset:1536 sc0 sc1
	global_store_dword v2, v1, s[4:5] offset:1664 sc0 sc1
	global_store_dword v2, v1, s[4:5] offset:1792 sc0 sc1
	global_store_dword v2, v1, s[4:5] offset:1920 sc0 sc1
	global_store_dword v2, v1, s[4:5] offset:2048 sc0 sc1
	v_mov_b32_e32 v2, 0x7d00000
	v_mov_b32_e32 v3, 0x7d01000
	global_store_dword v2, v1, s[82:83] offset:0 sc0 sc1
	global_store_dword v2, v1, s[82:83] offset:128 sc0 sc1
	global_store_dword v2, v1, s[82:83] offset:256 sc0 sc1
	global_store_dword v2, v1, s[82:83] offset:384 sc0 sc1
	global_store_dword v2, v1, s[82:83] offset:512 sc0 sc1
	global_store_dword v2, v1, s[82:83] offset:640 sc0 sc1
	global_store_dword v2, v1, s[82:83] offset:768 sc0 sc1
	global_store_dword v2, v1, s[82:83] offset:896 sc0 sc1
	global_store_dword v2, v1, s[82:83] offset:1024 sc0 sc1
	global_store_dword v2, v1, s[82:83] offset:1152 sc0 sc1
	global_store_dword v2, v1, s[82:83] offset:1280 sc0 sc1
	global_store_dword v2, v1, s[82:83] offset:1408 sc0 sc1
	global_store_dword v2, v1, s[82:83] offset:1536 sc0 sc1
	global_store_dword v2, v1, s[82:83] offset:1664 sc0 sc1
	global_store_dword v2, v1, s[82:83] offset:1792 sc0 sc1
	global_store_dword v2, v1, s[82:83] offset:1920 sc0 sc1
	global_store_dword v2, v1, s[82:83] offset:2048 sc0 sc1
	global_store_dword v2, v1, s[82:83] offset:2176 sc0 sc1
	global_store_dword v2, v1, s[82:83] offset:2304 sc0 sc1
	global_store_dword v2, v1, s[82:83] offset:2432 sc0 sc1
	global_store_dword v2, v1, s[82:83] offset:2560 sc0 sc1
	global_store_dword v2, v1, s[82:83] offset:2688 sc0 sc1
	global_store_dword v2, v1, s[82:83] offset:2816 sc0 sc1
	global_store_dword v2, v1, s[82:83] offset:2944 sc0 sc1
	global_store_dword v2, v1, s[82:83] offset:3072 sc0 sc1
	global_store_dword v2, v1, s[82:83] offset:3200 sc0 sc1
	global_store_dword v2, v1, s[82:83] offset:3328 sc0 sc1
	global_store_dword v2, v1, s[82:83] offset:3456 sc0 sc1
	global_store_dword v2, v1, s[82:83] offset:3584 sc0 sc1
	global_store_dword v2, v1, s[82:83] offset:3712 sc0 sc1
	global_store_dword v2, v1, s[82:83] offset:3840 sc0 sc1
	global_store_dword v2, v1, s[82:83] offset:3968 sc0 sc1
	global_store_dword v3, v1, s[82:83] offset:0 sc0 sc1
	global_store_dword v3, v1, s[82:83] offset:128 sc0 sc1
	global_store_dword v3, v1, s[82:83] offset:256 sc0 sc1
	global_store_dword v3, v1, s[82:83] offset:384 sc0 sc1
	global_store_dword v3, v1, s[82:83] offset:512 sc0 sc1
	global_store_dword v3, v1, s[82:83] offset:640 sc0 sc1
	global_store_dword v3, v1, s[82:83] offset:768 sc0 sc1
	global_store_dword v3, v1, s[82:83] offset:896 sc0 sc1
	global_store_dword v3, v1, s[82:83] offset:1024 sc0 sc1
	global_store_dword v3, v1, s[82:83] offset:1152 sc0 sc1
	global_store_dword v3, v1, s[82:83] offset:1280 sc0 sc1
	global_store_dword v3, v1, s[82:83] offset:1408 sc0 sc1
	global_store_dword v3, v1, s[82:83] offset:1536 sc0 sc1
	global_store_dword v3, v1, s[82:83] offset:1664 sc0 sc1
	global_store_dword v3, v1, s[82:83] offset:1792 sc0 sc1
	global_store_dword v3, v1, s[82:83] offset:1920 sc0 sc1
	global_store_dword v3, v1, s[82:83] offset:2048 sc0 sc1
	global_store_dword v3, v1, s[82:83] offset:2176 sc0 sc1
	global_store_dword v3, v1, s[82:83] offset:2304 sc0 sc1
	global_store_dword v3, v1, s[82:83] offset:2432 sc0 sc1
	global_store_dword v3, v1, s[82:83] offset:2560 sc0 sc1
	global_store_dword v3, v1, s[82:83] offset:2688 sc0 sc1
	global_store_dword v3, v1, s[82:83] offset:2816 sc0 sc1
	global_store_dword v3, v1, s[82:83] offset:2944 sc0 sc1
	global_store_dword v3, v1, s[82:83] offset:3072 sc0 sc1
	global_store_dword v3, v1, s[82:83] offset:3200 sc0 sc1
	global_store_dword v3, v1, s[82:83] offset:3328 sc0 sc1
	global_store_dword v3, v1, s[82:83] offset:3456 sc0 sc1
	global_store_dword v3, v1, s[82:83] offset:3584 sc0 sc1
	global_store_dword v3, v1, s[82:83] offset:3712 sc0 sc1
	global_store_dword v3, v1, s[82:83] offset:3840 sc0 sc1
	global_store_dword v3, v1, s[82:83] offset:3968 sc0 sc1
	s_waitcnt vmcnt(0) lgkmcnt(0)
	v_mov_b32_e32 v2, 1
	global_atomic_add v1, v2, s[100:101] offset:32

;     __device__ bool next(int i, Unit& u) const {
;         const long L = (long)i * G + c; if (L >= nwg) return false;
;         int wgid = (int)L; { const int q = nwg / NXCD, r = nwg % NXCD, xcd = wgid % NXCD, off = wgid / NXCD; wgid = (xcd < r ? xcd * (q + 1) : r * (q + 1) + (xcd - r) * q) + off; }
;         const int nig = WGM * nN, gid = wgid / nig, fm = gid * WGM, gsz = (nM - fm) < WGM ? (nM - fm) : WGM;
;         u.pm = fm + ((wgid % nig) % gsz); u.pn = (wgid % nig) / gsz; return true;
; __global__ void __launch_bounds__(512, 2) hymba_fwd(Params p) {
;     ...
;         pg8::Gemm g{MIX, (const h16*)(ws + OFF_WT_OUT), MP, D, D};
;         pg8::StaticOrder S; S.init(MP, D, G, c);
;         { pg8::Unit u0; for (int i = 0; S.next(i, u0); ++i) groupnorm_rows(p, u0.pm * 256, u0.pm * 256 + 256); }
.LBB0_391:
	s_ashr_i32 s4, s6, 3
	s_add_i32 s4, s12, s4
	s_bfe_u32 s98, s4, 0x20003
	s_ashr_i32 s5, s4, 31
	s_lshr_b32 s5, s5, 27
	s_add_i32 s5, s4, s5
	s_ashr_i32 s6, s5, 5
	s_lshl_b32 s6, s6, 3
	s_sub_i32 s7, 64, s6
	s_min_i32 s7, s7, 8
	s_abs_i32 s7, s7
	v_cvt_f32_u32_e32 v0, s7
	s_sub_i32 s12, 0, s7
	s_andn2_b32 s5, s5, 31
	s_sub_i32 s4, s4, s5
	v_rcp_iflag_f32_e32 v0, v0
	s_ashr_i32 s5, s4, 31
	s_abs_i32 s4, s4
	v_mul_f32_e32 v0, 0x4f7ffffe, v0
	v_cvt_u32_f32_e32 v0, v0
	s_nop 0
	v_readfirstlane_b32 s13, v0
	s_mul_i32 s12, s12, s13
	s_mul_hi_u32 s12, s13, s12
	s_add_i32 s13, s13, s12
	s_mul_hi_u32 s12, s4, s13
	s_mul_i32 s12, s12, s7
	s_sub_i32 s4, s4, s12
	s_sub_i32 s12, s4, s7
	s_cmp_ge_u32 s4, s7
	s_cselect_b32 s4, s12, s4
	s_sub_i32 s12, s4, s7
	s_cmp_ge_u32 s4, s7
	s_cselect_b32 s4, s12, s4
	s_xor_b32 s4, s4, s5
	s_sub_i32 s4, s4, s5
	s_add_i32 s20, s6, s4
	v_cmp_lt_i64_e32 vcc, s[0:1], v[68:69]
	s_mov_b64 s[0:1], -1
	s_cbranch_vccz .LBB0_384
.LBB0_392:
	global_load_dwordx4 v[0:3], v[52:53], off offset:16
	global_load_dwordx4 v[4:7], v[52:53], off
	global_load_dwordx4 v[8:11], v[54:55], off offset:16
	global_load_dwordx4 v[12:15], v[54:55], off
	v_cmp_lt_i32_e32 vcc, v89, v135
	s_lshl_b32 s0, s20, 8
	s_lshl_b32 s99, s98, 6
	s_cmpk_eq_i32 s33, 0x100
	s_cselect_b32 s99, s99, 0
	s_add_i32 s0, s0, s99
	v_or_b32_e32 v72, s0, v142
	s_waitcnt vmcnt(5)
	v_cndmask_b32_e32 v16, v129, v89, vcc
	v_lshlrev_b32_e32 v90, 2, v16
	v_or_b32_e32 v16, s0, v86
	v_ashrrev_i32_e32 v17, 31, v16
	v_lshlrev_b64 v[16:17], 11, v[16:17]
	v_lshl_add_u64 v[74:75], v[62:63], 0, v[16:17]
	v_or_b32_e32 v16, s0, v87
	v_ashrrev_i32_e32 v17, 31, v16
	v_lshlrev_b64 v[16:17], 11, v[16:17]
	v_ashrrev_i32_e32 v73, 31, v72
	v_lshl_add_u64 v[76:77], v[62:63], 0, v[16:17]
	v_lshlrev_b64 v[16:17], 11, v[72:73]
	v_lshl_add_u64 v[78:79], v[62:63], 0, v[16:17]
	v_lshl_add_u64 v[80:81], v[64:65], 0, v[16:17]
	v_lshlrev_b64 v[16:17], 10, v[72:73]
	s_cmpk_eq_i32 s33, 0x100
	s_cselect_b32 s21, 64, 0x100
	s_add_i32 s21, s21, s0
	v_lshl_add_u64 v[82:83], v[66:67], 0, v[16:17]
	s_mov_b64 s[12:13], 0
	s_mov_b64 s[14:15], 0
	s_branch .LBB0_394

; __device__ __forceinline__ void groupnorm_rows(const Params& p, int rbeg, int rend) {
;     ...
;     for (int row0 = rbeg + wave; row0 < rend; row0 += 4 * stride) {
;         f32x4 ya[4], yb[4]; h16x8 gg[4];
; #pragma unroll
;         for (int u = 0; u < 4; ++u) {
;             const int r = row0 + u * stride, rc = r < rend ? r : row0;
;             ya[u] = *(const f32x4*)(YRAW + (size_t)rc * 512 + c); yb[u] = *(const f32x4*)(YRAW + (size_t)rc * 512 + c + 4);
;             gg[u] = *(const h16x8*)(G16 + (size_t)rc * 512 + c);
;         }
; #pragma unroll
;         for (int u = 0; u < 4; ++u) {
;             const int row = row0 + u * stride;
;             f32x4 y0 = ya[u], y1 = yb[u];
;             float s = y0[0] + y0[1] + y0[2] + y0[3] + y1[0] + y1[1] + y1[2] + y1[3];
;             s = dpp_add<0xB1>(s); s = dpp_add<0x4E>(s); s += __shfl_xor(s, 4);
;             const float mu = s * (1.f / 64.f);
;             y0 -= mu; y1 -= mu;
;             float q = y0[0] * y0[0] + y0[1] * y0[1] + y0[2] * y0[2] + y0[3] * y0[3] + y1[0] * y1[0] + y1[1] * y1[1] + y1[2] * y1[2] + y1[3] * y1[3];
;             q = dpp_add<0xB1>(q); q = dpp_add<0x4E>(q); q += __shfl_xor(q, 4);
;             const float rstd = rsqrtf(q * (1.f / 64.f) + GN_EPS);
;             f32x4 o0, o1;
; #pragma unroll
;             for (int j = 0; j < 4; ++j) { o0[j] = (y0[j] * rstd * w0[j] + b0[j]) * (float)gg[u][j]; o1[j] = (y1[j] * rstd * w1[j] + b1[j]) * (float)gg[u][4 + j]; }
;             if (row < rend) *(h16x8*)(MIX + (size_t)row * D + 512 + c) = pack8(o0, o1);
.LBB0_394:
	v_lshl_add_u64 v[16:17], v[80:81], 0, s[14:15]
	v_lshl_add_u64 v[18:19], v[16:17], 0, s[8:9]
	v_add_co_u32_e32 v16, vcc, 0x8620000, v16
	global_load_dwordx4 v[92:95], v[82:83], off
	s_nop 0
	v_addc_co_u32_e32 v17, vcc, 0, v17, vcc
	global_load_dwordx4 v[96:99], v[16:17], off
	v_add_u32_e32 v16, 8, v72
	v_cmp_gt_i32_e64 s[6:7], s21, v16
	v_add_u32_e32 v84, 24, v72
	v_cmp_gt_i32_e32 vcc, s21, v84
	v_cndmask_b32_e64 v16, v72, v16, s[6:7]
	v_ashrrev_i32_e32 v17, 31, v16
	s_waitcnt vmcnt(6)
	v_lshlrev_b64 v[20:21], 11, v[16:17]
	v_lshl_add_u64 v[20:21], v[56:57], 0, v[20:21]
	global_load_dwordx4 v[48:51], v[20:21], off
	global_load_dwordx4 v[100:103], v[18:19], off offset:16
	global_load_dwordx4 v[40:43], v[20:21], off offset:16
	v_add_u32_e32 v18, 16, v72
	v_cmp_gt_i32_e64 s[4:5], s21, v18
	v_cndmask_b32_e32 v20, v72, v84, vcc
	v_ashrrev_i32_e32 v21, 31, v20
	v_cndmask_b32_e64 v18, v72, v18, s[4:5]
	v_ashrrev_i32_e32 v19, 31, v18
	v_lshlrev_b64 v[16:17], 10, v[16:17]
	v_lshlrev_b64 v[22:23], 11, v[18:19]
	v_lshlrev_b64 v[18:19], 10, v[18:19]
	s_waitcnt vmcnt(6)
	v_lshlrev_b64 v[24:25], 11, v[20:21]
	v_lshlrev_b64 v[20:21], 10, v[20:21]
	v_lshl_add_u64 v[104:105], v[60:61], 0, v[16:17]
	v_lshl_add_u64 v[106:107], v[56:57], 0, v[22:23]
	v_lshl_add_u64 v[108:109], v[60:61], 0, v[18:19]
	v_lshl_add_u64 v[110:111], v[56:57], 0, v[24:25]
	v_lshl_add_u64 v[112:113], v[60:61], 0, v[20:21]
	global_load_dwordx4 v[44:47], v[104:105], off
	s_waitcnt lgkmcnt(0)
	global_load_dwordx4 v[28:31], v[106:107], off offset:16
	global_load_dwordx4 v[32:35], v[106:107], off
	global_load_dwordx4 v[36:39], v[108:109], off
	global_load_dwordx4 v[16:19], v[110:111], off offset:16
	global_load_dwordx4 v[20:23], v[110:111], off
	global_load_dwordx4 v[24:27], v[112:113], off
	s_waitcnt vmcnt(11)
	v_cvt_f32_f16_sdwa v105, v92 dst_sel:DWORD dst_unused:UNUSED_PAD src0_sel:WORD_1
	v_cvt_f32_f16_e32 v104, v92
	v_cvt_f32_f16_sdwa v107, v93 dst_sel:DWORD dst_unused:UNUSED_PAD src0_sel:WORD_1
	s_waitcnt vmcnt(10)
	v_add_f32_e32 v73, v96, v97
	v_add_f32_e32 v73, v98, v73
	v_add_f32_e32 v73, v99, v73
	v_cvt_f32_f16_e32 v106, v93
	v_cvt_f32_f16_sdwa v93, v94 dst_sel:DWORD dst_unused:UNUSED_PAD src0_sel:WORD_1
	v_cvt_f32_f16_e32 v92, v94
	v_cvt_f32_f16_sdwa v109, v95 dst_sel:DWORD dst_unused:UNUSED_PAD src0_sel:WORD_1
	s_waitcnt vmcnt(9)
	v_add_f32_e32 v85, v48, v49
	s_waitcnt vmcnt(8)
	v_add_f32_e32 v73, v100, v73
	v_add_f32_e32 v85, v50, v85
	v_add_f32_e32 v73, v101, v73
	v_add_f32_e32 v85, v51, v85
	v_add_f32_e32 v73, v102, v73
	s_waitcnt vmcnt(7)
	v_add_f32_e32 v85, v40, v85
	v_add_f32_e32 v73, v103, v73
	v_add_f32_e32 v85, v41, v85
	v_add_f32_e32 v85, v42, v85
	v_add_f32_dpp v73, v73, v73 quad_perm:[1,0,3,2] row_mask:0xf bank_mask:0xf bound_ctrl:1
	v_add_f32_e32 v85, v43, v85
	v_cvt_f32_f16_e32 v108, v95
	v_add_f32_dpp v73, v73, v73 quad_perm:[2,3,0,1] row_mask:0xf bank_mask:0xf bound_ctrl:1
	ds_bpermute_b32 v91, v90, v73
	v_add_f32_dpp v85, v85, v85 quad_perm:[1,0,3,2] row_mask:0xf bank_mask:0xf bound_ctrl:1
	s_waitcnt lgkmcnt(0)
	v_add_f32_e32 v73, v73, v91
	v_add_f32_dpp v85, v85, v85 quad_perm:[2,3,0,1] row_mask:0xf bank_mask:0xf bound_ctrl:1
	ds_bpermute_b32 v116, v90, v85
	v_fmamk_f32 v95, v73, 0xbc800000, v97
	v_fmamk_f32 v94, v73, 0xbc800000, v96
	v_fmamk_f32 v99, v73, 0xbc800000, v99
	v_fmac_f32_e32 v98, 0xbc800000, v73
	v_pk_mul_f32 v[110:111], v[94:95], v[94:95]
	v_fmamk_f32 v97, v73, 0xbc800000, v101
	v_fmamk_f32 v96, v73, 0xbc800000, v100
	v_fmamk_f32 v103, v73, 0xbc800000, v103
	v_fmac_f32_e32 v102, 0xbc800000, v73
	v_pk_mul_f32 v[100:101], v[98:99], v[98:99]
	s_waitcnt lgkmcnt(0)
	v_add_f32_e32 v73, v85, v116
	v_add_f32_e32 v85, v110, v111
	v_add_f32_e32 v85, v100, v85
	v_pk_mul_f32 v[114:115], v[96:97], v[96:97]
	v_add_f32_e32 v85, v101, v85
	v_add_f32_e32 v85, v114, v85
	v_pk_mul_f32 v[112:113], v[102:103], v[102:103]
	v_add_f32_e32 v85, v115, v85
	v_add_f32_e32 v85, v112, v85
	v_add_f32_e32 v85, v113, v85
	v_fmamk_f32 v51, v73, 0xbc800000, v51
	v_fmamk_f32 v50, v73, 0xbc800000, v50
	v_add_f32_dpp v85, v85, v85 quad_perm:[1,0,3,2] row_mask:0xf bank_mask:0xf bound_ctrl:1
	v_fmamk_f32 v49, v73, 0xbc800000, v49
	v_fmac_f32_e32 v48, 0xbc800000, v73
	v_add_f32_dpp v85, v85, v85 quad_perm:[2,3,0,1] row_mask:0xf bank_mask:0xf bound_ctrl:1
	ds_bpermute_b32 v91, v90, v85
	v_fmamk_f32 v43, v73, 0xbc800000, v43
	v_fmamk_f32 v42, v73, 0xbc800000, v42
	v_fmamk_f32 v41, v73, 0xbc800000, v41
	v_fmac_f32_e32 v40, 0xbc800000, v73
	s_waitcnt lgkmcnt(0)
	v_add_f32_e32 v73, v85, v91
	v_fmamk_f32 v73, v73, 0x3c800000, v88
	v_mul_f32_e32 v85, 0x4b800000, v73
	v_cmp_gt_f32_e64 s[0:1], s19, v73
	s_nop 1
	v_cndmask_b32_e64 v73, v73, v85, s[0:1]
	v_mul_f32_e32 v85, v49, v49
	v_fmac_f32_e32 v85, v48, v48
	v_fmac_f32_e32 v85, v50, v50
	v_rsq_f32_e32 v73, v73
	v_fmac_f32_e32 v85, v51, v51
	v_fmac_f32_e32 v85, v40, v40
	v_fmac_f32_e32 v85, v41, v41
	v_fmac_f32_e32 v85, v42, v42
	v_mul_f32_e32 v91, 0x45800000, v73
	v_fmac_f32_e32 v85, v43, v43
	v_cndmask_b32_e64 v100, v73, v91, s[0:1]
	v_pk_mul_f32 v[94:95], v[94:95], v[100:101] op_sel_hi:[1,0]
	v_add_f32_dpp v73, v85, v85 quad_perm:[1,0,3,2] row_mask:0xf bank_mask:0xf bound_ctrl:1
	v_pk_mul_f32 v[96:97], v[96:97], v[100:101] op_sel_hi:[1,0]
	v_pk_mul_f32 v[98:99], v[98:99], v[100:101] op_sel_hi:[1,0]
	v_add_f32_dpp v73, v73, v73 quad_perm:[2,3,0,1] row_mask:0xf bank_mask:0xf bound_ctrl:1
	ds_bpermute_b32 v85, v90, v73
	v_pk_mul_f32 v[100:101], v[102:103], v[100:101] op_sel_hi:[1,0]
	v_pk_fma_f32 v[94:95], v[12:13], v[94:95], v[4:5]
	v_pk_fma_f32 v[96:97], v[8:9], v[96:97], v[0:1]
	v_pk_fma_f32 v[98:99], v[14:15], v[98:99], v[6:7]
	v_pk_fma_f32 v[100:101], v[10:11], v[100:101], v[2:3]
	v_pk_mul_f32 v[94:95], v[94:95], v[104:105]
	v_pk_mul_f32 v[96:97], v[96:97], v[92:93]
	v_pk_mul_f32 v[98:99], v[98:99], v[106:107]
	v_cvt_pk_f16_f32 v92, v94, v95
	v_cvt_pk_f16_f32 v94, v96, v97
	v_pk_mul_f32 v[96:97], v[100:101], v[108:109]
	v_cvt_pk_f16_f32 v93, v98, v99
	v_cvt_pk_f16_f32 v95, v96, v97
	v_lshl_add_u64 v[96:97], v[78:79], 0, s[14:15]
	global_store_dwordx4 v[96:97], v[92:95], off sc0 sc1
	s_and_saveexec_b64 s[16:17], s[6:7]
	s_cbranch_execz .LBB0_396
; __device__ __forceinline__ void groupnorm_rows(const Params& p, int rbeg, int rend) {
;     ...
; #pragma unroll
;         for (int u = 0; u < 4; ++u) {
;             const int row = row0 + u * stride;
;             f32x4 y0 = ya[u], y1 = yb[u];
;             float s = y0[0] + y0[1] + y0[2] + y0[3] + y1[0] + y1[1] + y1[2] + y1[3];
;             s = dpp_add<0xB1>(s); s = dpp_add<0x4E>(s); s += __shfl_xor(s, 4);
;             const float mu = s * (1.f / 64.f);
;             y0 -= mu; y1 -= mu;
;             float q = y0[0] * y0[0] + y0[1] * y0[1] + y0[2] * y0[2] + y0[3] * y0[3] + y1[0] * y1[0] + y1[1] * y1[1] + y1[2] * y1[2] + y1[3] * y1[3];
;             q = dpp_add<0xB1>(q); q = dpp_add<0x4E>(q); q += __shfl_xor(q, 4);
;             const float rstd = rsqrtf(q * (1.f / 64.f) + GN_EPS);
;             f32x4 o0, o1;
; #pragma unroll
;             for (int j = 0; j < 4; ++j) { o0[j] = (y0[j] * rstd * w0[j] + b0[j]) * (float)gg[u][j]; o1[j] = (y1[j] * rstd * w1[j] + b1[j]) * (float)gg[u][4 + j]; }
;             if (row < rend) *(h16x8*)(MIX + (size_t)row * D + 512 + c) = pack8(o0, o1);
	s_waitcnt lgkmcnt(0)
	v_add_f32_e32 v73, v73, v85
	v_fmamk_f32 v73, v73, 0x3c800000, v88
	v_mul_f32_e32 v85, 0x4b800000, v73
	v_cmp_gt_f32_e64 s[0:1], s19, v73
	s_waitcnt vmcnt(7)
	v_cvt_f32_f16_sdwa v93, v44 dst_sel:DWORD dst_unused:UNUSED_PAD src0_sel:WORD_1
	v_cvt_f32_f16_e32 v92, v44
	v_cndmask_b32_e64 v73, v73, v85, s[0:1]
	v_rsq_f32_e32 v73, v73
	s_nop 0
	v_mul_f32_e32 v44, 0x45800000, v73
	v_cndmask_b32_e64 v94, v73, v44, s[0:1]
	v_pk_mul_f32 v[48:49], v[48:49], v[94:95] op_sel_hi:[1,0]
	v_pk_mul_f32 v[40:41], v[40:41], v[94:95] op_sel_hi:[1,0]
	v_pk_fma_f32 v[48:49], v[12:13], v[48:49], v[4:5]
	v_pk_fma_f32 v[40:41], v[8:9], v[40:41], v[0:1]
	v_pk_mul_f32 v[48:49], v[48:49], v[92:93]
	v_cvt_f32_f16_sdwa v93, v45 dst_sel:DWORD dst_unused:UNUSED_PAD src0_sel:WORD_1
	v_cvt_f32_f16_e32 v92, v45
	v_cvt_pk_f16_f32 v44, v48, v49
	v_pk_mul_f32 v[48:49], v[50:51], v[94:95] op_sel_hi:[1,0]
	v_cvt_f32_f16_sdwa v51, v46 dst_sel:DWORD dst_unused:UNUSED_PAD src0_sel:WORD_1
	v_cvt_f32_f16_e32 v50, v46
	v_pk_fma_f32 v[48:49], v[14:15], v[48:49], v[6:7]
	v_pk_mul_f32 v[40:41], v[40:41], v[50:51]
	v_pk_mul_f32 v[48:49], v[48:49], v[92:93]
	v_cvt_pk_f16_f32 v46, v40, v41
	v_cvt_pk_f16_f32 v45, v48, v49
	v_cvt_f32_f16_sdwa v49, v47 dst_sel:DWORD dst_unused:UNUSED_PAD src0_sel:WORD_1
	v_cvt_f32_f16_e32 v48, v47
	v_pk_mul_f32 v[40:41], v[42:43], v[94:95] op_sel_hi:[1,0]
	s_nop 0
	v_pk_fma_f32 v[40:41], v[10:11], v[40:41], v[2:3]
	s_nop 0
	v_pk_mul_f32 v[40:41], v[40:41], v[48:49]
	s_nop 0
	v_cvt_pk_f16_f32 v47, v40, v41
	v_lshl_add_u64 v[40:41], v[76:77], 0, s[14:15]
	global_store_dwordx4 v[40:41], v[44:47], off sc0 sc1
.LBB0_396:
	s_or_b64 exec, exec, s[16:17]
	s_waitcnt vmcnt(5)
	v_add_f32_e32 v40, v32, v33
	v_add_f32_e32 v40, v34, v40
	v_add_f32_e32 v40, v35, v40
	v_add_f32_e32 v40, v28, v40
	v_add_f32_e32 v40, v29, v40
	v_add_f32_e32 v40, v30, v40
	v_add_f32_e32 v40, v31, v40
	s_nop 1
	v_add_f32_dpp v40, v40, v40 quad_perm:[1,0,3,2] row_mask:0xf bank_mask:0xf bound_ctrl:1
	s_nop 1
	v_add_f32_dpp v40, v40, v40 quad_perm:[2,3,0,1] row_mask:0xf bank_mask:0xf bound_ctrl:1
	ds_bpermute_b32 v41, v90, v40
	s_waitcnt lgkmcnt(0)
	v_add_f32_e32 v40, v40, v41
	v_fmamk_f32 v33, v40, 0xbc800000, v33
	v_fmamk_f32 v35, v40, 0xbc800000, v35
	v_fmamk_f32 v34, v40, 0xbc800000, v34
	v_fmac_f32_e32 v32, 0xbc800000, v40
	v_fmamk_f32 v31, v40, 0xbc800000, v31
	v_fmamk_f32 v30, v40, 0xbc800000, v30
	v_fmamk_f32 v29, v40, 0xbc800000, v29
	v_fmac_f32_e32 v28, 0xbc800000, v40
	v_mul_f32_e32 v40, v33, v33
	v_fmac_f32_e32 v40, v32, v32
	v_fmac_f32_e32 v40, v34, v34
	v_fmac_f32_e32 v40, v35, v35
	v_fmac_f32_e32 v40, v28, v28
	v_fmac_f32_e32 v40, v29, v29
	v_fmac_f32_e32 v40, v30, v30
	v_fmac_f32_e32 v40, v31, v31
	s_nop 1
	v_add_f32_dpp v40, v40, v40 quad_perm:[1,0,3,2] row_mask:0xf bank_mask:0xf bound_ctrl:1
	s_nop 1
	v_add_f32_dpp v40, v40, v40 quad_perm:[2,3,0,1] row_mask:0xf bank_mask:0xf bound_ctrl:1
	ds_bpermute_b32 v41, v90, v40
	s_and_saveexec_b64 s[6:7], s[4:5]
	s_cbranch_execz .LBB0_398
	s_waitcnt lgkmcnt(0)
	v_add_f32_e32 v40, v40, v41
	v_fmamk_f32 v40, v40, 0x3c800000, v88
	v_mul_f32_e32 v41, 0x4b800000, v40
	v_cmp_gt_f32_e64 s[0:1], s19, v40
	s_waitcnt vmcnt(4)
	v_cvt_f32_f16_sdwa v45, v37 dst_sel:DWORD dst_unused:UNUSED_PAD src0_sel:WORD_1
	v_cvt_f32_f16_e32 v44, v37
	v_cndmask_b32_e64 v40, v40, v41, s[0:1]
	v_rsq_f32_e32 v42, v40
	v_cvt_f32_f16_sdwa v41, v39 dst_sel:DWORD dst_unused:UNUSED_PAD src0_sel:WORD_1
	v_cvt_f32_f16_e32 v40, v39
	v_cvt_f32_f16_sdwa v37, v38 dst_sel:DWORD dst_unused:UNUSED_PAD src0_sel:WORD_1
	v_mul_f32_e32 v39, 0x45800000, v42
	v_cvt_f32_f16_sdwa v47, v36 dst_sel:DWORD dst_unused:UNUSED_PAD src0_sel:WORD_1
	v_cvt_f32_f16_e32 v46, v36
	v_cvt_f32_f16_e32 v36, v38
	v_cndmask_b32_e64 v42, v42, v39, s[0:1]
	v_pk_mul_f32 v[32:33], v[32:33], v[42:43] op_sel_hi:[1,0]
	v_pk_mul_f32 v[34:35], v[34:35], v[42:43] op_sel_hi:[1,0]
	v_pk_mul_f32 v[28:29], v[28:29], v[42:43] op_sel_hi:[1,0]
	v_pk_fma_f32 v[32:33], v[12:13], v[32:33], v[4:5]
	v_pk_fma_f32 v[34:35], v[14:15], v[34:35], v[6:7]
	v_pk_fma_f32 v[28:29], v[8:9], v[28:29], v[0:1]
	v_pk_mul_f32 v[32:33], v[32:33], v[46:47]
	v_pk_mul_f32 v[34:35], v[34:35], v[44:45]
	v_pk_mul_f32 v[28:29], v[28:29], v[36:37]
	v_cvt_pk_f16_f32 v32, v32, v33
	v_cvt_pk_f16_f32 v33, v34, v35
	v_cvt_pk_f16_f32 v34, v28, v29
	v_pk_mul_f32 v[28:29], v[30:31], v[42:43] op_sel_hi:[1,0]
	s_nop 0
	v_pk_fma_f32 v[28:29], v[10:11], v[28:29], v[2:3]
	s_nop 0
	v_pk_mul_f32 v[28:29], v[28:29], v[40:41]
	s_nop 0
	v_cvt_pk_f16_f32 v35, v28, v29
	v_lshl_add_u64 v[28:29], v[74:75], 0, s[14:15]
	global_store_dwordx4 v[28:29], v[32:35], off sc0 sc1
; __device__ __forceinline__ void groupnorm_rows(const Params& p, int rbeg, int rend) {
;     ...
;             for (int j = 0; j < 4; ++j) { o0[j] = (y0[j] * rstd * w0[j] + b0[j]) * (float)gg[u][j]; o1[j] = (y1[j] * rstd * w1[j] + b1[j]) * (float)gg[u][4 + j]; }
;             if (row < rend) *(h16x8*)(MIX + (size_t)row * D + 512 + c) = pack8(o0, o1);
;         }
;     }
; __global__ void __launch_bounds__(512, 2) hymba_fwd(Params p) {
;     ...
;         { pg8::Unit u0; for (int i = 0; S.next(i, u0); ++i) groupnorm_rows(p, u0.pm * 256, u0.pm * 256 + 256); }
;         asm volatile("s_waitcnt vmcnt(0)" ::: "memory");
;         __syncthreads();
.LBB0_398:
	s_or_b64 exec, exec, s[6:7]
	s_waitcnt vmcnt(2)
	v_add_f32_e32 v28, v20, v21
	v_add_f32_e32 v28, v22, v28
	v_add_f32_e32 v28, v23, v28
	v_add_f32_e32 v28, v16, v28
	v_add_f32_e32 v28, v17, v28
	v_add_f32_e32 v28, v18, v28
	v_add_f32_e32 v28, v19, v28
	s_nop 1
	v_add_f32_dpp v28, v28, v28 quad_perm:[1,0,3,2] row_mask:0xf bank_mask:0xf bound_ctrl:1
	s_nop 1
	v_add_f32_dpp v28, v28, v28 quad_perm:[2,3,0,1] row_mask:0xf bank_mask:0xf bound_ctrl:1
	ds_bpermute_b32 v29, v90, v28
	s_waitcnt lgkmcnt(0)
	v_add_f32_e32 v28, v28, v29
	v_fmamk_f32 v21, v28, 0xbc800000, v21
	v_fmamk_f32 v23, v28, 0xbc800000, v23
	v_fmamk_f32 v22, v28, 0xbc800000, v22
	v_fmac_f32_e32 v20, 0xbc800000, v28
	v_fmamk_f32 v19, v28, 0xbc800000, v19
	v_fmamk_f32 v18, v28, 0xbc800000, v18
	v_fmamk_f32 v17, v28, 0xbc800000, v17
	v_fmac_f32_e32 v16, 0xbc800000, v28
	v_mul_f32_e32 v28, v21, v21
	v_fmac_f32_e32 v28, v20, v20
	v_fmac_f32_e32 v28, v22, v22
	v_fmac_f32_e32 v28, v23, v23
	v_fmac_f32_e32 v28, v16, v16
	v_fmac_f32_e32 v28, v17, v17
	v_fmac_f32_e32 v28, v18, v18
	v_fmac_f32_e32 v28, v19, v19
	s_nop 1
	v_add_f32_dpp v28, v28, v28 quad_perm:[1,0,3,2] row_mask:0xf bank_mask:0xf bound_ctrl:1
	s_nop 1
	v_add_f32_dpp v28, v28, v28 quad_perm:[2,3,0,1] row_mask:0xf bank_mask:0xf bound_ctrl:1
	ds_bpermute_b32 v29, v90, v28
	s_and_saveexec_b64 s[0:1], vcc
	s_cbranch_execz .LBB0_393
	s_waitcnt lgkmcnt(0)
	v_add_f32_e32 v28, v28, v29
	v_fmamk_f32 v28, v28, 0x3c800000, v88
	v_mul_f32_e32 v29, 0x4b800000, v28
	v_cmp_gt_f32_e32 vcc, s19, v28
	s_waitcnt vmcnt(1)
	v_cvt_f32_f16_sdwa v33, v25 dst_sel:DWORD dst_unused:UNUSED_PAD src0_sel:WORD_1
	v_cvt_f32_f16_e32 v32, v25
	v_cndmask_b32_e32 v28, v28, v29, vcc
	v_rsq_f32_e32 v30, v28
	v_cvt_f32_f16_sdwa v29, v27 dst_sel:DWORD dst_unused:UNUSED_PAD src0_sel:WORD_1
	v_cvt_f32_f16_e32 v28, v27
	v_cvt_f32_f16_sdwa v25, v26 dst_sel:DWORD dst_unused:UNUSED_PAD src0_sel:WORD_1
	v_mul_f32_e32 v27, 0x45800000, v30
	v_cvt_f32_f16_sdwa v35, v24 dst_sel:DWORD dst_unused:UNUSED_PAD src0_sel:WORD_1
	v_cvt_f32_f16_e32 v34, v24
	v_cvt_f32_f16_e32 v24, v26
	v_cndmask_b32_e32 v30, v30, v27, vcc
	v_pk_mul_f32 v[20:21], v[20:21], v[30:31] op_sel_hi:[1,0]
	v_pk_mul_f32 v[22:23], v[22:23], v[30:31] op_sel_hi:[1,0]
	v_pk_mul_f32 v[16:17], v[16:17], v[30:31] op_sel_hi:[1,0]
	v_pk_fma_f32 v[20:21], v[12:13], v[20:21], v[4:5]
	v_pk_fma_f32 v[22:23], v[14:15], v[22:23], v[6:7]
	v_pk_fma_f32 v[16:17], v[8:9], v[16:17], v[0:1]
	v_pk_mul_f32 v[20:21], v[20:21], v[34:35]
	v_pk_mul_f32 v[22:23], v[22:23], v[32:33]
	v_pk_mul_f32 v[16:17], v[16:17], v[24:25]
	v_cvt_pk_f16_f32 v20, v20, v21
	v_cvt_pk_f16_f32 v21, v22, v23
	v_cvt_pk_f16_f32 v22, v16, v17
	v_pk_mul_f32 v[16:17], v[18:19], v[30:31] op_sel_hi:[1,0]
	v_ashrrev_i32_e32 v85, 31, v84
	v_pk_fma_f32 v[16:17], v[10:11], v[16:17], v[2:3]
	s_nop 0
	v_pk_mul_f32 v[16:17], v[16:17], v[28:29]
	s_nop 0
	v_cvt_pk_f16_f32 v23, v16, v17
	v_lshlrev_b64 v[16:17], 11, v[84:85]
	v_lshl_add_u64 v[16:17], v[58:59], 0, v[16:17]
	global_store_dwordx4 v[16:17], v[20:23], off offset:1024 sc0 sc1
	s_branch .LBB0_393
.LBB0_400:
	s_waitcnt vmcnt(0)
	s_waitcnt vmcnt(3)
	v_mov_b32_e32 v8, v132
	v_cndmask_b32_e64 v0, 0, 1, s[76:77]
	s_waitcnt lgkmcnt(0)
	s_barrier
	s_cmpk_lg_i32 s33, 0x100
	s_cbranch_scc1 .Lgn_nosync
	v_cmp_eq_u32_e32 vcc, 0, v132
	s_and_saveexec_b64 s[100:101], vcc
	s_cbranch_execz .Lgn_sync_end
	s_lshl_b32 s97, s20, 7
	s_add_i32 s97, s97, 0x7d00000
	v_mov_b32_e32 v2, s97
	v_mov_b32_e32 v3, 1
	s_waitcnt vmcnt(0)
	global_atomic_add v2, v3, s[82:83]
.Lgn_poll:
	s_sleep 1
	global_load_dword v4, v2, s[82:83] sc1
	s_waitcnt vmcnt(0)
	v_readfirstlane_b32 s97, v4
	s_cmp_lt_u32 s97, 4
	s_cbranch_scc1 .Lgn_poll
.Lgn_sync_end:
	s_or_b64 exec, exec, s[100:101]
	s_barrier
.Lgn_nosync:
	v_cmp_ne_u32_e64 s[4:5], 1, v0
	s_andn2_b64 vcc, exec, s[76:77]
	v_readfirstlane_b32 s34, v8
	s_cbranch_vccnz .LBB0_410
	s_lshr_b32 s0, s3, 29
	s_add_i32 s6, s2, s0
	s_and_b32 s0, s6, -8
	s_sub_i32 s7, s2, s0
	s_cmp_gt_i32 s7, -1
	s_cbranch_scc0 .LBB0_407
	s_lshl_b32 s8, s7, 5
	s_cbranch_execz .LBB0_408
	s_branch .LBB0_409
